# up epilogue: half of the H stores (pattern 0011 per 4) use the default write-back policy, the other half stay nt (split the burst between L2 and the fabric), on top of v59
# baseline (speedup 1.0000x reference)
; __device__ __forceinline__ unsigned cvt_pk_bf16(float lo, float hi) { unsigned r; asm volatile("v_cvt_pk_bf16_f32 %0, %1, %2" : "=v"(r) : "v"(lo), "v"(hi)); return r; }
;     __device__ __forceinline__ void operator()(const f32x4 (&acc)[2][2][4][2], const Unit& u, int ui, int wr, int wc, int fr, int fq) const {
;         asm volatile("" : "+v"(fr), "+v"(fq));
;         if (skip) return;
;         const int row0 = u.pm * BM + wr * 64 + fr, col0 = u.pn * HALF + wc * 32 + 8 * fq;
;         float rs[2][4];
; #pragma unroll
;         for (int ai = 0; ai < 2; ++ai)
; #pragma unroll
;             for (int m = 0; m < 4; ++m) rs[ai][m] = row_rstd(lds, ui, ai * HALF + wr * 64 + m * 16 + fr);
; #pragma unroll
;         for (int ai = 0; ai < 2; ++ai)
; #pragma unroll
;             for (int m = 0; m < 4; ++m) { const float r = rs[ai][m]; const int row = row0 + ai * HALF + m * 16;
;                 const float c1 = r * -1.44269504089f, r2 = r * r; u32x4 w;
; #pragma unroll
;                 for (int n = 0; n < 2; ++n)
; #pragma unroll
;                     for (int p = 0; p < 2; ++p) { const f32x2 g = (f32x2){acc[ai][0][m][n][2 * p], acc[ai][0][m][n][2 * p + 1]}, uu = (f32x2){acc[ai][1][m][n][2 * p], acc[ai][1][m][n][2 * p + 1]};
;                         const f32x2 t = g * c1; f32x2 d; d.x = __builtin_amdgcn_exp2f(t.x); d.y = __builtin_amdgcn_exp2f(t.y); d = d + 1.0f;
;                         f32x2 q; q.x = __builtin_amdgcn_rcpf(d.x); q.y = __builtin_amdgcn_rcpf(d.y);
;                         const f32x2 hh = (g * uu) * (q * r2); w[2 * n + p] = cvt_pk_bf16(hh.x, hh.y); }
;                 __builtin_nontemporal_store(w, (u32x4*)(H + (size_t)row * ldh + col0)); }
.LBB0_449:
	v_mov_b32_e32 v140, v147
	v_mov_b32_e32 v167, v164
	v_pk_mul_f32 v[120:121], v[124:125], v[120:121]
	v_add_u32_e32 v171, s35, v140
	v_lshlrev_b32_e32 v140, 2, v171
	v_lshl_add_u32 v140, s48, 10, v140
	v_add_u32_e32 v140, 0x20400, v140
	ds_read2_b32 v[168:169], v140 offset1:16
	ds_read2_b32 v[162:163], v140 offset0:32 offset1:48
	ds_read2_b32 v[142:143], v140 offset0:128 offset1:144
	ds_read2_b32 v[140:141], v140 offset0:160 offset1:176
	v_pk_mul_f32 v[122:123], v[126:127], v[122:123]
	s_waitcnt lgkmcnt(0)
	v_mul_f32_e32 v172, 0xbfb8aa3b, v168
	v_pk_mul_f32 v[174:175], v[124:125], v[172:173] op_sel_hi:[1,0]
	v_pk_mul_f32 v[124:125], v[126:127], v[172:173] op_sel_hi:[1,0]
	v_exp_f32_e32 v174, v174
	v_exp_f32_e32 v175, v175
	v_exp_f32_e32 v124, v124
	v_exp_f32_e32 v125, v125
	v_mul_f32_e32 v168, v168, v168
	v_pk_add_f32 v[174:175], v[174:175], 1.0 op_sel_hi:[1,0]
	v_pk_mul_f32 v[112:113], v[116:117], v[112:113]
	v_rcp_f32_e32 v174, v174
	v_rcp_f32_e32 v175, v175
	v_pk_add_f32 v[124:125], v[124:125], 1.0 op_sel_hi:[1,0]
	v_pk_mul_f32 v[114:115], v[118:119], v[114:115]
	v_rcp_f32_e32 v124, v124
	v_rcp_f32_e32 v125, v125
	v_pk_mul_f32 v[126:127], v[168:169], v[174:175] op_sel_hi:[0,1]
	v_pk_mul_f32 v[120:121], v[120:121], v[126:127]
	v_pk_mul_f32 v[126:127], v[116:117], v[172:173] op_sel_hi:[1,0]
	v_pk_mul_f32 v[124:125], v[168:169], v[124:125] op_sel_hi:[0,1]
	v_exp_f32_e32 v126, v126
	v_exp_f32_e32 v127, v127
	v_pk_mul_f32 v[122:123], v[122:123], v[124:125]
	v_pk_mul_f32 v[124:125], v[118:119], v[172:173] op_sel_hi:[1,0]
	v_cvt_pk_bf16_f32 v120, v120, v121
	v_cvt_pk_bf16_f32 v121, v122, v123
	v_pk_add_f32 v[122:123], v[126:127], 1.0 op_sel_hi:[1,0]
	v_exp_f32_e32 v124, v124
	v_exp_f32_e32 v125, v125
	v_rcp_f32_e32 v122, v122
	v_rcp_f32_e32 v123, v123
	s_lshl_b32 s5, s47, 7
	v_pk_add_f32 v[116:117], v[124:125], 1.0 op_sel_hi:[1,0]
	s_or_b32 s5, s5, s36
	v_rcp_f32_e32 v116, v116
	v_rcp_f32_e32 v117, v117
	v_pk_mul_f32 v[118:119], v[168:169], v[122:123] op_sel_hi:[0,1]
	v_pk_mul_f32 v[112:113], v[112:113], v[118:119]
	v_mul_f32_e32 v118, 0xbfb8aa3b, v169
	v_cvt_pk_bf16_f32 v122, v112, v113
	v_pk_mul_f32 v[112:113], v[168:169], v[116:117] op_sel_hi:[0,1]
	v_pk_mul_f32 v[124:125], v[108:109], v[118:119] op_sel_hi:[1,0]
	v_lshl_add_u32 v170, v167, 3, s5
	v_pk_mul_f32 v[112:113], v[114:115], v[112:113]
	v_exp_f32_e32 v124, v124
	v_exp_f32_e32 v125, v125
	v_lshl_add_u32 v167, s46, 8, v171
	v_ashrrev_i32_e32 v171, 31, v170
	v_cvt_pk_bf16_f32 v123, v112, v113
	v_mov_b64_e32 v[112:113], s[20:21]
	v_pk_mul_f32 v[104:105], v[108:109], v[104:105]
	v_pk_mul_f32 v[108:109], v[110:111], v[118:119] op_sel_hi:[1,0]
	v_mad_i64_i32 v[116:117], s[14:15], v167, s59, v[112:113]
	v_lshlrev_b64 v[114:115], 1, v[170:171]
	v_exp_f32_e32 v108, v108
	v_exp_f32_e32 v109, v109
	v_lshl_add_u64 v[116:117], v[116:117], 0, v[114:115]
	global_store_dwordx4 v[116:117], v[120:123], off nt
	v_mul_f32_e32 v116, v169, v169
	v_pk_add_f32 v[108:109], v[108:109], 1.0 op_sel_hi:[1,0]
	v_pk_add_f32 v[120:121], v[124:125], 1.0 op_sel_hi:[1,0]
	v_rcp_f32_e32 v108, v108
	v_rcp_f32_e32 v120, v120
	v_rcp_f32_e32 v121, v121
	v_rcp_f32_e32 v109, v109
	v_pk_mul_f32 v[106:107], v[110:111], v[106:107]
	v_pk_mul_f32 v[96:97], v[100:101], v[96:97]
	v_pk_mul_f32 v[110:111], v[116:117], v[120:121] op_sel_hi:[0,1]
	v_pk_mul_f32 v[104:105], v[104:105], v[110:111]
	v_pk_mul_f32 v[110:111], v[100:101], v[118:119] op_sel_hi:[1,0]
	v_pk_mul_f32 v[108:109], v[116:117], v[108:109] op_sel_hi:[0,1]
	v_exp_f32_e32 v110, v110
	v_exp_f32_e32 v111, v111
	v_pk_mul_f32 v[106:107], v[106:107], v[108:109]
	v_pk_mul_f32 v[108:109], v[102:103], v[118:119] op_sel_hi:[1,0]
	v_cvt_pk_bf16_f32 v104, v104, v105
	v_cvt_pk_bf16_f32 v105, v106, v107
	v_pk_add_f32 v[106:107], v[110:111], 1.0 op_sel_hi:[1,0]
	v_exp_f32_e32 v108, v108
	v_exp_f32_e32 v109, v109
	v_rcp_f32_e32 v106, v106
	v_rcp_f32_e32 v107, v107
	v_pk_mul_f32 v[98:99], v[102:103], v[98:99]
	v_pk_add_f32 v[100:101], v[108:109], 1.0 op_sel_hi:[1,0]
	v_pk_mul_f32 v[88:89], v[92:93], v[88:89]
	v_rcp_f32_e32 v100, v100
	v_rcp_f32_e32 v101, v101
	v_pk_mul_f32 v[102:103], v[116:117], v[106:107] op_sel_hi:[0,1]
	v_pk_mul_f32 v[96:97], v[96:97], v[102:103]
	v_pk_mul_f32 v[90:91], v[94:95], v[90:91]
	v_cvt_pk_bf16_f32 v106, v96, v97
	v_pk_mul_f32 v[96:97], v[116:117], v[100:101] op_sel_hi:[0,1]
	v_pk_mul_f32 v[96:97], v[98:99], v[96:97]
	v_mul_f32_e32 v98, 0xbfb8aa3b, v162
	v_pk_mul_f32 v[100:101], v[92:93], v[98:99] op_sel_hi:[1,0]
	v_pk_mul_f32 v[92:93], v[94:95], v[98:99] op_sel_hi:[1,0]
	v_exp_f32_e32 v100, v100
	v_exp_f32_e32 v101, v101
	v_exp_f32_e32 v92, v92
	v_exp_f32_e32 v93, v93
	v_cvt_pk_bf16_f32 v107, v96, v97
	v_pk_add_f32 v[100:101], v[100:101], 1.0 op_sel_hi:[1,0]
	v_add_u32_e32 v96, 16, v167
	v_rcp_f32_e32 v100, v100
	v_rcp_f32_e32 v101, v101
	v_mad_i64_i32 v[96:97], s[14:15], v96, s59, v[112:113]
	v_pk_add_f32 v[92:93], v[92:93], 1.0 op_sel_hi:[1,0]
	v_lshl_add_u64 v[96:97], v[96:97], 0, v[114:115]
	v_rcp_f32_e32 v92, v92
	v_rcp_f32_e32 v93, v93
	global_store_dwordx4 v[96:97], v[104:107], off nt
	v_mul_f32_e32 v96, v162, v162
	v_pk_mul_f32 v[94:95], v[96:97], v[100:101] op_sel_hi:[0,1]
	v_pk_mul_f32 v[88:89], v[88:89], v[94:95]
	v_pk_mul_f32 v[94:95], v[84:85], v[98:99] op_sel_hi:[1,0]
	v_pk_mul_f32 v[92:93], v[96:97], v[92:93] op_sel_hi:[0,1]
	v_exp_f32_e32 v94, v94
	v_exp_f32_e32 v95, v95
	v_pk_mul_f32 v[90:91], v[90:91], v[92:93]
	v_pk_mul_f32 v[92:93], v[86:87], v[98:99] op_sel_hi:[1,0]
	v_cvt_pk_bf16_f32 v88, v88, v89
	v_cvt_pk_bf16_f32 v89, v90, v91
	v_pk_add_f32 v[90:91], v[94:95], 1.0 op_sel_hi:[1,0]
	v_exp_f32_e32 v92, v92
; __device__ __forceinline__ unsigned cvt_pk_bf16(float lo, float hi) { unsigned r; asm volatile("v_cvt_pk_bf16_f32 %0, %1, %2" : "=v"(r) : "v"(lo), "v"(hi)); return r; }
;     __device__ __forceinline__ void operator()(const f32x4 (&acc)[2][2][4][2], const Unit& u, int ui, int wr, int wc, int fr, int fq) const {
;     ...
;             for (int m = 0; m < 4; ++m) { const float r = rs[ai][m]; const int row = row0 + ai * HALF + m * 16;
;                 const float c1 = r * -1.44269504089f, r2 = r * r; u32x4 w;
; #pragma unroll
;                 for (int n = 0; n < 2; ++n)
; #pragma unroll
;                     for (int p = 0; p < 2; ++p) { const f32x2 g = (f32x2){acc[ai][0][m][n][2 * p], acc[ai][0][m][n][2 * p + 1]}, uu = (f32x2){acc[ai][1][m][n][2 * p], acc[ai][1][m][n][2 * p + 1]};
;                         const f32x2 t = g * c1; f32x2 d; d.x = __builtin_amdgcn_exp2f(t.x); d.y = __builtin_amdgcn_exp2f(t.y); d = d + 1.0f;
;                         f32x2 q; q.x = __builtin_amdgcn_rcpf(d.x); q.y = __builtin_amdgcn_rcpf(d.y);
;                         const f32x2 hh = (g * uu) * (q * r2); w[2 * n + p] = cvt_pk_bf16(hh.x, hh.y); }
;                 __builtin_nontemporal_store(w, (u32x4*)(H + (size_t)row * ldh + col0)); }
	v_exp_f32_e32 v93, v93
	v_rcp_f32_e32 v90, v90
	v_rcp_f32_e32 v91, v91
	v_pk_mul_f32 v[80:81], v[84:85], v[80:81]
	v_pk_add_f32 v[84:85], v[92:93], 1.0 op_sel_hi:[1,0]
	v_pk_mul_f32 v[82:83], v[86:87], v[82:83]
	v_rcp_f32_e32 v84, v84
	v_rcp_f32_e32 v85, v85
	v_pk_mul_f32 v[86:87], v[96:97], v[90:91] op_sel_hi:[0,1]
	v_pk_mul_f32 v[80:81], v[80:81], v[86:87]
	v_pk_mul_f32 v[72:73], v[76:77], v[72:73]
	v_cvt_pk_bf16_f32 v90, v80, v81
	v_pk_mul_f32 v[80:81], v[96:97], v[84:85] op_sel_hi:[0,1]
	v_pk_mul_f32 v[80:81], v[82:83], v[80:81]
	v_mul_f32_e32 v82, 0xbfb8aa3b, v163
	v_pk_mul_f32 v[84:85], v[76:77], v[82:83] op_sel_hi:[1,0]
	v_pk_mul_f32 v[76:77], v[78:79], v[82:83] op_sel_hi:[1,0]
	v_exp_f32_e32 v84, v84
	v_exp_f32_e32 v85, v85
	v_exp_f32_e32 v76, v76
	v_exp_f32_e32 v77, v77
	v_cvt_pk_bf16_f32 v91, v80, v81
	v_pk_add_f32 v[84:85], v[84:85], 1.0 op_sel_hi:[1,0]
	v_add_u32_e32 v80, 32, v167
	v_rcp_f32_e32 v84, v84
	v_rcp_f32_e32 v85, v85
	v_mad_i64_i32 v[80:81], s[14:15], v80, s59, v[112:113]
	v_pk_add_f32 v[76:77], v[76:77], 1.0 op_sel_hi:[1,0]
	v_lshl_add_u64 v[80:81], v[80:81], 0, v[114:115]
	v_rcp_f32_e32 v76, v76
	v_rcp_f32_e32 v77, v77
	global_store_dwordx4 v[80:81], v[88:91], off
	v_mul_f32_e32 v80, v163, v163
	v_pk_mul_f32 v[74:75], v[78:79], v[74:75]
	v_pk_mul_f32 v[78:79], v[80:81], v[84:85] op_sel_hi:[0,1]
	v_pk_mul_f32 v[72:73], v[72:73], v[78:79]
	v_pk_mul_f32 v[78:79], v[68:69], v[82:83] op_sel_hi:[1,0]
	v_pk_mul_f32 v[76:77], v[80:81], v[76:77] op_sel_hi:[0,1]
	v_exp_f32_e32 v78, v78
	v_exp_f32_e32 v79, v79
	v_pk_mul_f32 v[74:75], v[74:75], v[76:77]
	v_pk_mul_f32 v[76:77], v[70:71], v[82:83] op_sel_hi:[1,0]
	v_cvt_pk_bf16_f32 v72, v72, v73
	v_cvt_pk_bf16_f32 v73, v74, v75
	v_pk_add_f32 v[74:75], v[78:79], 1.0 op_sel_hi:[1,0]
	v_exp_f32_e32 v76, v76
	v_exp_f32_e32 v77, v77
	v_rcp_f32_e32 v74, v74
	v_rcp_f32_e32 v75, v75
	v_pk_mul_f32 v[64:65], v[68:69], v[64:65]
	v_pk_add_f32 v[68:69], v[76:77], 1.0 op_sel_hi:[1,0]
	v_pk_mul_f32 v[66:67], v[70:71], v[66:67]
	v_rcp_f32_e32 v68, v68
	v_rcp_f32_e32 v69, v69
	v_pk_mul_f32 v[70:71], v[80:81], v[74:75] op_sel_hi:[0,1]
	v_pk_mul_f32 v[64:65], v[64:65], v[70:71]
	v_pk_mul_f32 v[56:57], v[60:61], v[56:57]
	v_cvt_pk_bf16_f32 v74, v64, v65
	v_pk_mul_f32 v[64:65], v[80:81], v[68:69] op_sel_hi:[0,1]
	v_pk_mul_f32 v[64:65], v[66:67], v[64:65]
	v_mul_f32_e32 v66, 0xbfb8aa3b, v142
	v_pk_mul_f32 v[68:69], v[60:61], v[66:67] op_sel_hi:[1,0]
	v_pk_mul_f32 v[60:61], v[62:63], v[66:67] op_sel_hi:[1,0]
	v_exp_f32_e32 v68, v68
	v_exp_f32_e32 v69, v69
	v_exp_f32_e32 v60, v60
	v_exp_f32_e32 v61, v61
	v_cvt_pk_bf16_f32 v75, v64, v65
	v_pk_add_f32 v[68:69], v[68:69], 1.0 op_sel_hi:[1,0]
	v_add_u32_e32 v64, 48, v167
	v_rcp_f32_e32 v68, v68
	v_rcp_f32_e32 v69, v69
	v_mad_i64_i32 v[64:65], s[14:15], v64, s59, v[112:113]
	v_pk_add_f32 v[60:61], v[60:61], 1.0 op_sel_hi:[1,0]
	v_lshl_add_u64 v[64:65], v[64:65], 0, v[114:115]
	v_rcp_f32_e32 v60, v60
	v_rcp_f32_e32 v61, v61
	global_store_dwordx4 v[64:65], v[72:75], off
	v_add_u32_e32 v65, 0x80, v167
	v_mul_f32_e32 v64, v142, v142
	v_pk_mul_f32 v[58:59], v[62:63], v[58:59]
	v_pk_mul_f32 v[62:63], v[64:65], v[68:69] op_sel_hi:[0,1]
	v_pk_mul_f32 v[56:57], v[56:57], v[62:63]
	v_pk_mul_f32 v[62:63], v[52:53], v[66:67] op_sel_hi:[1,0]
	v_pk_mul_f32 v[60:61], v[64:65], v[60:61] op_sel_hi:[0,1]
	v_exp_f32_e32 v62, v62
	v_exp_f32_e32 v63, v63
	v_pk_mul_f32 v[58:59], v[58:59], v[60:61]
	v_pk_mul_f32 v[60:61], v[54:55], v[66:67] op_sel_hi:[1,0]
	v_cvt_pk_bf16_f32 v56, v56, v57
	v_cvt_pk_bf16_f32 v57, v58, v59
	v_pk_add_f32 v[58:59], v[62:63], 1.0 op_sel_hi:[1,0]
	v_exp_f32_e32 v60, v60
	v_exp_f32_e32 v61, v61
	v_rcp_f32_e32 v58, v58
	v_rcp_f32_e32 v59, v59
	v_pk_mul_f32 v[48:49], v[52:53], v[48:49]
	v_pk_add_f32 v[52:53], v[60:61], 1.0 op_sel_hi:[1,0]
	v_pk_mul_f32 v[50:51], v[54:55], v[50:51]
	v_rcp_f32_e32 v52, v52
	v_rcp_f32_e32 v53, v53
	v_pk_mul_f32 v[54:55], v[64:65], v[58:59] op_sel_hi:[0,1]
	v_pk_mul_f32 v[48:49], v[48:49], v[54:55]
	v_pk_mul_f32 v[40:41], v[44:45], v[40:41]
	v_cvt_pk_bf16_f32 v58, v48, v49
	v_pk_mul_f32 v[48:49], v[64:65], v[52:53] op_sel_hi:[0,1]
	v_pk_mul_f32 v[48:49], v[50:51], v[48:49]
	v_mul_f32_e32 v50, 0xbfb8aa3b, v143
	v_pk_mul_f32 v[52:53], v[44:45], v[50:51] op_sel_hi:[1,0]
	v_pk_mul_f32 v[44:45], v[46:47], v[50:51] op_sel_hi:[1,0]
	v_exp_f32_e32 v52, v52
	v_exp_f32_e32 v53, v53
	v_exp_f32_e32 v44, v44
	v_exp_f32_e32 v45, v45
	v_cvt_pk_bf16_f32 v59, v48, v49
	v_pk_add_f32 v[52:53], v[52:53], 1.0 op_sel_hi:[1,0]
	v_mad_i64_i32 v[48:49], s[14:15], v65, s59, v[112:113]
	v_rcp_f32_e32 v52, v52
	v_rcp_f32_e32 v53, v53
	v_pk_add_f32 v[44:45], v[44:45], 1.0 op_sel_hi:[1,0]
	v_lshl_add_u64 v[48:49], v[48:49], 0, v[114:115]
	v_rcp_f32_e32 v44, v44
	v_rcp_f32_e32 v45, v45
	global_store_dwordx4 v[48:49], v[56:59], off nt
	v_mul_f32_e32 v48, v143, v143
	v_pk_mul_f32 v[42:43], v[46:47], v[42:43]
; __device__ __forceinline__ unsigned cvt_pk_bf16(float lo, float hi) { unsigned r; asm volatile("v_cvt_pk_bf16_f32 %0, %1, %2" : "=v"(r) : "v"(lo), "v"(hi)); return r; }
;     __device__ __forceinline__ void operator()(const f32x4 (&acc)[2][2][4][2], const Unit& u, int ui, int wr, int wc, int fr, int fq) const {
;     ...
;             for (int m = 0; m < 4; ++m) { const float r = rs[ai][m]; const int row = row0 + ai * HALF + m * 16;
;                 const float c1 = r * -1.44269504089f, r2 = r * r; u32x4 w;
; #pragma unroll
;                 for (int n = 0; n < 2; ++n)
; #pragma unroll
;                     for (int p = 0; p < 2; ++p) { const f32x2 g = (f32x2){acc[ai][0][m][n][2 * p], acc[ai][0][m][n][2 * p + 1]}, uu = (f32x2){acc[ai][1][m][n][2 * p], acc[ai][1][m][n][2 * p + 1]};
;                         const f32x2 t = g * c1; f32x2 d; d.x = __builtin_amdgcn_exp2f(t.x); d.y = __builtin_amdgcn_exp2f(t.y); d = d + 1.0f;
;                         f32x2 q; q.x = __builtin_amdgcn_rcpf(d.x); q.y = __builtin_amdgcn_rcpf(d.y);
;                         const f32x2 hh = (g * uu) * (q * r2); w[2 * n + p] = cvt_pk_bf16(hh.x, hh.y); }
;                 __builtin_nontemporal_store(w, (u32x4*)(H + (size_t)row * ldh + col0)); }
	v_pk_mul_f32 v[46:47], v[48:49], v[52:53] op_sel_hi:[0,1]
	v_pk_mul_f32 v[40:41], v[40:41], v[46:47]
	v_pk_mul_f32 v[46:47], v[36:37], v[50:51] op_sel_hi:[1,0]
	v_pk_mul_f32 v[44:45], v[48:49], v[44:45] op_sel_hi:[0,1]
	v_exp_f32_e32 v46, v46
	v_exp_f32_e32 v47, v47
	v_pk_mul_f32 v[42:43], v[42:43], v[44:45]
	v_pk_mul_f32 v[44:45], v[38:39], v[50:51] op_sel_hi:[1,0]
	v_cvt_pk_bf16_f32 v40, v40, v41
	v_cvt_pk_bf16_f32 v41, v42, v43
	v_pk_add_f32 v[42:43], v[46:47], 1.0 op_sel_hi:[1,0]
	v_exp_f32_e32 v44, v44
	v_exp_f32_e32 v45, v45
	v_rcp_f32_e32 v42, v42
	v_rcp_f32_e32 v43, v43
	v_pk_mul_f32 v[32:33], v[36:37], v[32:33]
	v_pk_add_f32 v[36:37], v[44:45], 1.0 op_sel_hi:[1,0]
	v_pk_mul_f32 v[34:35], v[38:39], v[34:35]
	v_rcp_f32_e32 v36, v36
	v_rcp_f32_e32 v37, v37
	v_pk_mul_f32 v[38:39], v[48:49], v[42:43] op_sel_hi:[0,1]
	v_pk_mul_f32 v[32:33], v[32:33], v[38:39]
	v_pk_mul_f32 v[24:25], v[28:29], v[24:25]
	v_cvt_pk_bf16_f32 v42, v32, v33
	v_pk_mul_f32 v[32:33], v[48:49], v[36:37] op_sel_hi:[0,1]
	v_pk_mul_f32 v[32:33], v[34:35], v[32:33]
	v_mul_f32_e32 v34, 0xbfb8aa3b, v140
	v_pk_mul_f32 v[36:37], v[28:29], v[34:35] op_sel_hi:[1,0]
	v_pk_mul_f32 v[28:29], v[30:31], v[34:35] op_sel_hi:[1,0]
	v_exp_f32_e32 v36, v36
	v_exp_f32_e32 v37, v37
	v_exp_f32_e32 v28, v28
	v_exp_f32_e32 v29, v29
	v_cvt_pk_bf16_f32 v43, v32, v33
	v_pk_add_f32 v[36:37], v[36:37], 1.0 op_sel_hi:[1,0]
	v_add_u32_e32 v32, 0x90, v167
	v_rcp_f32_e32 v36, v36
	v_rcp_f32_e32 v37, v37
	v_mad_i64_i32 v[32:33], s[14:15], v32, s59, v[112:113]
	v_pk_add_f32 v[28:29], v[28:29], 1.0 op_sel_hi:[1,0]
	v_lshl_add_u64 v[32:33], v[32:33], 0, v[114:115]
	v_rcp_f32_e32 v28, v28
	v_rcp_f32_e32 v29, v29
	global_store_dwordx4 v[32:33], v[40:43], off nt
	v_mul_f32_e32 v32, v140, v140
	v_pk_mul_f32 v[26:27], v[30:31], v[26:27]
	v_pk_mul_f32 v[30:31], v[32:33], v[36:37] op_sel_hi:[0,1]
	v_pk_mul_f32 v[24:25], v[24:25], v[30:31]
	v_pk_mul_f32 v[30:31], v[20:21], v[34:35] op_sel_hi:[1,0]
	v_pk_mul_f32 v[28:29], v[32:33], v[28:29] op_sel_hi:[0,1]
	v_exp_f32_e32 v30, v30
	v_exp_f32_e32 v31, v31
	v_pk_mul_f32 v[26:27], v[26:27], v[28:29]
	v_pk_mul_f32 v[28:29], v[22:23], v[34:35] op_sel_hi:[1,0]
	v_cvt_pk_bf16_f32 v24, v24, v25
	v_cvt_pk_bf16_f32 v25, v26, v27
	v_pk_add_f32 v[26:27], v[30:31], 1.0 op_sel_hi:[1,0]
	v_exp_f32_e32 v28, v28
	v_exp_f32_e32 v29, v29
	v_rcp_f32_e32 v26, v26
	v_rcp_f32_e32 v27, v27
	v_pk_mul_f32 v[16:17], v[20:21], v[16:17]
	v_pk_add_f32 v[20:21], v[28:29], 1.0 op_sel_hi:[1,0]
	v_pk_mul_f32 v[18:19], v[22:23], v[18:19]
	v_rcp_f32_e32 v20, v20
	v_rcp_f32_e32 v21, v21
	v_pk_mul_f32 v[22:23], v[32:33], v[26:27] op_sel_hi:[0,1]
	v_pk_mul_f32 v[16:17], v[16:17], v[22:23]
	v_pk_mul_f32 v[8:9], v[12:13], v[8:9]
	v_cvt_pk_bf16_f32 v26, v16, v17
	v_pk_mul_f32 v[16:17], v[32:33], v[20:21] op_sel_hi:[0,1]
	v_pk_mul_f32 v[16:17], v[18:19], v[16:17]
	v_mul_f32_e32 v18, 0xbfb8aa3b, v141
	v_pk_mul_f32 v[20:21], v[12:13], v[18:19] op_sel_hi:[1,0]
	v_pk_mul_f32 v[12:13], v[14:15], v[18:19] op_sel_hi:[1,0]
	v_exp_f32_e32 v20, v20
	v_exp_f32_e32 v21, v21
	v_exp_f32_e32 v12, v12
	v_exp_f32_e32 v13, v13
	v_cvt_pk_bf16_f32 v27, v16, v17
	v_pk_add_f32 v[20:21], v[20:21], 1.0 op_sel_hi:[1,0]
	v_add_u32_e32 v16, 0xa0, v167
	v_rcp_f32_e32 v20, v20
	v_rcp_f32_e32 v21, v21
	v_mad_i64_i32 v[16:17], s[14:15], v16, s59, v[112:113]
	v_pk_add_f32 v[12:13], v[12:13], 1.0 op_sel_hi:[1,0]
	v_lshl_add_u64 v[16:17], v[16:17], 0, v[114:115]
	v_rcp_f32_e32 v12, v12
	v_rcp_f32_e32 v13, v13
	global_store_dwordx4 v[16:17], v[24:27], off
	v_mul_f32_e32 v16, v141, v141
	v_pk_mul_f32 v[10:11], v[14:15], v[10:11]
	v_pk_mul_f32 v[14:15], v[16:17], v[20:21] op_sel_hi:[0,1]
	v_pk_mul_f32 v[8:9], v[8:9], v[14:15]
	v_pk_mul_f32 v[14:15], v[4:5], v[18:19] op_sel_hi:[1,0]
	v_pk_mul_f32 v[12:13], v[16:17], v[12:13] op_sel_hi:[0,1]
	v_exp_f32_e32 v14, v14
	v_exp_f32_e32 v15, v15
	v_pk_mul_f32 v[10:11], v[10:11], v[12:13]
	v_pk_mul_f32 v[12:13], v[6:7], v[18:19] op_sel_hi:[1,0]
	v_cvt_pk_bf16_f32 v8, v8, v9
	v_cvt_pk_bf16_f32 v9, v10, v11
	v_pk_add_f32 v[10:11], v[14:15], 1.0 op_sel_hi:[1,0]
	v_exp_f32_e32 v12, v12
	v_exp_f32_e32 v13, v13
	v_rcp_f32_e32 v10, v10
	v_rcp_f32_e32 v11, v11
	v_pk_mul_f32 v[0:1], v[4:5], v[0:1]
	v_pk_add_f32 v[4:5], v[12:13], 1.0 op_sel_hi:[1,0]
	v_pk_mul_f32 v[2:3], v[6:7], v[2:3]
	v_rcp_f32_e32 v4, v4
	v_rcp_f32_e32 v5, v5
	v_pk_mul_f32 v[6:7], v[16:17], v[10:11] op_sel_hi:[0,1]
	v_pk_mul_f32 v[0:1], v[0:1], v[6:7]
	s_andn2_b64 vcc, exec, s[8:9]
	v_cvt_pk_bf16_f32 v10, v0, v1
	v_pk_mul_f32 v[0:1], v[16:17], v[4:5] op_sel_hi:[0,1]
	v_pk_mul_f32 v[0:1], v[2:3], v[0:1]
	s_mov_b64 s[8:9], -1
	v_cvt_pk_bf16_f32 v11, v0, v1
	v_add_u32_e32 v0, 0xb0, v167
	v_mad_i64_i32 v[0:1], s[14:15], v0, s59, v[112:113]
	v_lshl_add_u64 v[0:1], v[0:1], 0, v[114:115]
	global_store_dwordx4 v[0:1], v[8:11], off
	s_cbranch_vccnz .LBB0_442
	s_andn2_b64 vcc, exec, s[0:1]
	s_cbranch_vccnz .LBB0_441
	s_barrier
	s_branch .LBB0_441
